# attention no-mask bodies: in addition to the packed->scalar split, value-shuffling instructions removed (loop-invariant bpermute index hoisted to v255, dead index add, mov-then-add chains, fmac+mov ->
# baseline (speedup 1.0000x reference)
.LBB0_138:
	s_or_b64 exec, exec, s[0:1]
	s_add_u32 s34, s18, 0xb200000
	s_addc_u32 s35, s19, 0
	s_add_u32 s36, s18, 0xf200000
	s_addc_u32 s37, s19, 0
	s_add_u32 s0, s18, 0x3d00000
	s_addc_u32 s1, s19, 0
	v_writelane_b32 v251, s0, 55
	s_ashr_i32 s33, s12, 31
	s_ashr_i32 s23, s56, 31
	v_writelane_b32 v251, s1, 56
	s_add_u32 s0, s18, 0x3f00000
	s_addc_u32 s1, s19, 0
	v_writelane_b32 v251, s0, 57
	s_cmpk_lt_i32 s56, 0x800
	s_cselect_b64 s[46:47], -1, 0
	v_writelane_b32 v251, s1, 58
	s_lshr_b32 s0, s23, 29
	s_add_i32 s0, s56, s0
	s_ashr_i32 s1, s0, 3
	s_and_b32 s0, s0, -8
	s_sub_i32 s3, s56, s0
	s_lshl_b32 s4, s3, 8
	s_add_u32 s6, s18, 0x200
	s_addc_u32 s7, s19, 0
	s_add_u32 s20, s18, 0x1000
	s_addc_u32 s21, s19, 0
	s_add_u32 s14, s18, 0x1100
	s_addc_u32 s15, s19, 0
	s_add_u32 s26, s18, 0x1200
	s_addc_u32 s27, s19, 0
	s_add_u32 s24, s18, 0x1300
	s_addc_u32 s25, s19, 0
	v_writelane_b32 v251, s6, 59
	s_cmp_eq_u32 s39, 15
	s_mov_b32 s53, 0
	v_writelane_b32 v251, s7, 60
	s_cselect_b64 s[6:7], -1, 0
	v_writelane_b32 v251, s6, 61
	s_cmp_eq_u32 s39, 14
	s_mul_i32 s70, s13, s12
	v_writelane_b32 v251, s7, 62
	s_cselect_b64 s[6:7], -1, 0
	v_writelane_b32 v251, s6, 63
	s_cmp_eq_u32 s39, 13
	v_readlane_b32 s72, v251, 31
	v_writelane_b32 v252, s7, 0
	s_cselect_b64 s[6:7], -1, 0
	v_writelane_b32 v252, s6, 1
	s_cmp_eq_u32 s39, 12
	v_readlane_b32 s74, v251, 33
	v_writelane_b32 v252, s7, 2
	s_cselect_b64 s[6:7], -1, 0
	v_writelane_b32 v252, s6, 3
	s_cmp_eq_u32 s39, 11
	v_readlane_b32 s75, v251, 34
	v_writelane_b32 v252, s7, 4
	s_cselect_b64 s[6:7], -1, 0
	v_writelane_b32 v252, s6, 5
	s_cmp_eq_u32 s39, 10
	v_readlane_b32 s73, v251, 32
	v_writelane_b32 v252, s7, 6
	s_cselect_b64 s[6:7], -1, 0
	v_writelane_b32 v252, s6, 7
	s_cmp_eq_u32 s39, 9
	s_mul_i32 s70, s70, s38
	v_writelane_b32 v252, s7, 8
	s_cselect_b64 s[6:7], -1, 0
	v_writelane_b32 v252, s6, 9
	s_cmp_eq_u32 s39, 8
	s_mov_b32 s22, s56
	v_writelane_b32 v252, s7, 10
	s_cselect_b64 s[6:7], -1, 0
	v_writelane_b32 v252, s6, 11
	s_cmp_eq_u32 s39, 7
	v_mov_b64_e32 v[146:147], 0x7ff
	v_writelane_b32 v252, s7, 12
	s_cselect_b64 s[6:7], -1, 0
	v_writelane_b32 v252, s6, 13
	s_cmp_eq_u32 s39, 6
	v_mov_b32_e32 v198, 0x358637bd
	v_writelane_b32 v252, s7, 14
	s_cselect_b64 s[6:7], -1, 0
	v_writelane_b32 v252, s6, 15
	s_cmp_eq_u32 s39, 5
	v_mov_b32_e32 v199, 0x260
	v_writelane_b32 v252, s7, 16
	s_cselect_b64 s[6:7], -1, 0
	v_writelane_b32 v252, s6, 17
	s_cmp_eq_u32 s39, 4
	v_mov_b32_e32 v200, -1
	v_writelane_b32 v252, s7, 18
	s_cselect_b64 s[6:7], -1, 0
	v_writelane_b32 v252, s6, 19
	s_cmp_eq_u32 s39, 3
	v_mov_b32_e32 v1, 0
	v_writelane_b32 v252, s7, 20
	s_cselect_b64 s[6:7], -1, 0
	v_writelane_b32 v252, s6, 21
	s_cmp_eq_u32 s39, 2
	v_mov_b32_e32 v201, 1
	v_writelane_b32 v252, s7, 22
	s_cselect_b64 s[6:7], -1, 0
	v_writelane_b32 v252, s6, 23
	s_cmp_eq_u32 s39, 1
	v_mov_b32_e32 v202, 0x100
	v_writelane_b32 v252, s7, 24
	s_cselect_b64 s[6:7], -1, 0
	v_writelane_b32 v252, s6, 25
	s_cmp_eq_u32 s39, 0
	v_mov_b32_e32 v203, 0x200
	v_writelane_b32 v252, s7, 26
	s_cselect_b64 s[6:7], -1, 0
	s_lshl_b32 s0, s39, 8
	s_add_u32 s0, s18, s0
	v_writelane_b32 v252, s6, 27
	s_addc_u32 s2, s19, 0
	v_mov_b32_e32 v204, 0x300
	v_writelane_b32 v252, s7, 28
	s_add_u32 s6, s0, 0x1400
	s_addc_u32 s7, s2, 0
	v_writelane_b32 v252, s6, 29
	v_mov_b32_e32 v205, 0xffffc400
	v_mov_b32_e32 v206, 0xffffe200
	v_writelane_b32 v252, s7, 30
	s_add_u32 s6, s0, 0x2400
	s_addc_u32 s7, s2, 0
	v_writelane_b32 v252, s6, 31
	v_mbcnt_hi_u32_b32 v207, -1, v96
	v_xor_b32_e32 v255, 32, v207
	v_lshlrev_b32_e32 v255, 2, v255
	v_mov_b32_e32 v208, 0x7f800000
	v_writelane_b32 v252, s7, 32
	s_add_u32 s6, s18, 0x3400
	s_addc_u32 s7, s19, 0
	v_writelane_b32 v252, s6, 33
	v_mov_b32_e32 v209, 0x1e00
	v_mov_b32_e32 v210, 0xf149f2ca
	v_writelane_b32 v252, s7, 34
	s_add_u32 s6, s18, 0x3500
	s_addc_u32 s7, s19, 0
	v_writelane_b32 v252, s6, 35
	s_lshl_b32 s97, s12, 9
	s_lshl_b32 s0, s56, 9
	s_lshl_b32 s2, s12, 11
	v_writelane_b32 v252, s7, 36
	s_add_u32 s6, s18, 0x4200000
	v_writelane_b32 v252, s0, 37
	s_addc_u32 s7, s19, 0
	v_writelane_b32 v252, s6, 38
	s_lshl_b32 s0, s56, 4
	s_lshl_b32 s5, s56, 6
	v_writelane_b32 v252, s7, 39
	s_and_b32 s0, s0, 0xffffe000
	v_writelane_b32 v252, s5, 40
	s_and_b32 s5, s5, 0x1fc0
	s_or_b32 s0, s0, s5
	s_add_u32 s6, s18, 0x3f80000
	v_writelane_b32 v252, s0, 41
	s_addc_u32 s7, s19, 0
	v_writelane_b32 v252, s6, 42
	v_mov_b64_e32 v[150:151], 0x3ff
	v_mov_b64_e32 v[152:153], 0x400
	v_writelane_b32 v252, s7, 43
	s_add_u32 s6, s18, 0x4000000
	s_addc_u32 s7, s19, 0
	v_writelane_b32 v252, s6, 44
	s_cmpk_lt_i32 s56, 0x80
	v_mov_b64_e32 v[154:155], 0x100
	v_writelane_b32 v252, s7, 45
	s_cselect_b64 s[6:7], -1, 0
	v_writelane_b32 v252, s6, 46
	v_mov_b64_e32 v[156:157], 0xff
	v_mov_b64_e32 v[158:159], 0x200
	v_writelane_b32 v252, s7, 47
	s_add_u32 s6, s18, 0x4080000
	s_addc_u32 s7, s19, 0
	v_writelane_b32 v252, s6, 48
	v_mov_b64_e32 v[160:161], 0x1ff
	v_mov_b32_e32 v211, 0x1080
	v_writelane_b32 v252, s7, 49
	s_add_u32 s6, s18, 0x5200000
	s_addc_u32 s7, s19, 0
	v_writelane_b32 v252, s6, 50
	s_cmpk_lt_i32 s56, 0x400
	s_mov_b32 s71, s12
	v_writelane_b32 v252, s7, 51
	s_cselect_b64 s[6:7], -1, 0
	s_add_i32 s0, s12, 0xffffff80
	v_writelane_b32 v252, s6, 52
	s_cmp_ge_i32 s56, s0
	s_mov_b32 s72, 0x100000
	v_writelane_b32 v252, s7, 53
	s_cselect_b64 s[6:7], -1, 0
	s_sub_i32 s0, s56, s0
	v_writelane_b32 v252, s6, 54
	s_lshl_b32 s5, s0, 9
	s_lshl_b32 s0, s0, 4
	v_writelane_b32 v252, s7, 55
	s_and_b32 s5, s5, 0xe00
	s_and_b32 s0, s0, 0xffffff80
	v_writelane_b32 v252, s5, 56
	s_add_u32 s5, s18, 0xb000
	v_writelane_b32 v252, s5, 57
	s_addc_u32 s5, s19, 0
	v_writelane_b32 v252, s5, 58
	s_add_u32 s5, s18, 0x8000
	v_writelane_b32 v252, s5, 59
	s_addc_u32 s5, s19, 0
	s_add_u32 s68, s18, 0x900000
	v_writelane_b32 v252, s5, 60
	s_addc_u32 s69, s19, 0
	s_lshl_b32 s5, s3, 7
	s_add_u32 s6, s18, 0x1100000
	v_writelane_b32 v252, s6, 61
	s_addc_u32 s6, s19, 0
	s_cmpk_lt_i32 s56, 0x100
	v_writelane_b32 v252, s6, 62
	s_cselect_b64 s[6:7], -1, 0
	v_writelane_b32 v252, s6, 63
	s_mov_b32 s96, 0xf800000
	s_mov_b64 s[54:55], 0x80
	v_writelane_b32 v253, s7, 0
	s_lshl_b32 s6, s3, 5
	s_add_u32 s7, s18, 0x1900000
	v_writelane_b32 v253, s7, 1
	s_addc_u32 s7, s19, 0
	s_cmpk_lt_i32 s56, 0x200
	v_writelane_b32 v253, s7, 2
	s_cselect_b64 s[10:11], -1, 0
	v_writelane_b32 v253, s10, 3
	s_lshl_b32 s7, s3, 6
	v_readlane_b32 s76, v251, 35
	v_writelane_b32 v253, s11, 4
	s_add_u32 s10, s18, 0x2900000
	v_writelane_b32 v253, s10, 5
	s_addc_u32 s10, s19, 0
	v_writelane_b32 v253, s10, 6
	s_add_u32 s10, s18, 0x2100000
	v_writelane_b32 v253, s10, 7
	s_addc_u32 s10, s19, 0
	v_writelane_b32 v253, s10, 8
	s_cmp_lt_i32 s3, 0
	s_mul_i32 s10, s3, 0x101
	s_cselect_b32 s4, s10, s4
	s_mul_i32 s10, s3, 0x81
	s_cselect_b32 s10, s10, s5
	s_mul_i32 s5, s3, 33
	s_mulk_i32 s3, 0x41
	s_cselect_b32 s11, s5, s6
	s_cselect_b32 s3, s3, s7
	s_add_i32 s4, s4, s1
	s_ashr_i32 s5, s4, 31
	s_lshr_b32 s5, s5, 25
	s_add_i32 s5, s4, s5
	s_and_b32 s6, s5, 0xff80
	s_sub_i32 s4, s4, s6
	s_bfe_i32 s6, s4, 0x80000
	s_bfe_u32 s6, s6, 0x3000c
	s_add_i32 s6, s4, s6
	s_and_b32 s7, s6, 0xf8
	s_sub_i32 s4, s4, s7
	s_ashr_i32 s5, s5, 7
	s_bfe_i32 s6, s6, 0x80000
	s_lshl_b32 s5, s5, 3
	s_sext_i32_i16 s6, s6
	s_sext_i32_i8 s4, s4
	s_add_i32 s42, s5, s4
	s_ashr_i32 s4, s6, 3
	v_writelane_b32 v253, s4, 9
	s_lshr_b32 s4, s6, 3
	s_mov_b32 s6, s42
	s_ashr_i32 s43, s42, 31
	s_bfe_i64 s[4:5], s[4:5], 0x100000
	v_writelane_b32 v253, s6, 10
	s_lshl_b64 s[4:5], s[4:5], 19
	v_readlane_b32 s77, v251, 36
	v_writelane_b32 v253, s7, 11
	s_lshl_b64 s[6:7], s[42:43], 19
	v_readlane_b32 s42, v251, 29
	v_readlane_b32 s43, v251, 30
	s_add_u32 s4, s42, s4
	s_addc_u32 s5, s43, s5
	s_add_u32 s42, s4, 0x40000
	s_addc_u32 s43, s5, 0
	v_writelane_b32 v253, s42, 12
	s_add_u32 s6, s30, s6
	s_addc_u32 s7, s31, s7
	v_writelane_b32 v253, s43, 13
	s_add_u32 s42, s6, 0x40000
	v_writelane_b32 v253, s6, 14
	s_addc_u32 s43, s7, 0
	v_readlane_b32 s78, v251, 37
	v_writelane_b32 v253, s7, 15
	v_writelane_b32 v253, s42, 16
	s_add_u32 s6, s4, 0x40080
	v_readlane_b32 s79, v251, 38
	v_writelane_b32 v253, s43, 17
	v_writelane_b32 v253, s4, 18
	s_addc_u32 s7, s5, 0
	v_readlane_b32 s80, v251, 39
	v_writelane_b32 v253, s5, 19
	s_add_i32 s4, s10, s1
	s_ashr_i32 s5, s4, 31
	s_lshr_b32 s5, s5, 25
	v_writelane_b32 v253, s6, 20
	s_add_i32 s5, s4, s5
	v_readlane_b32 s81, v251, 40
	v_writelane_b32 v253, s7, 21
	s_and_b32 s6, s5, 0xff80
	s_sub_i32 s4, s4, s6
	s_bfe_i32 s6, s4, 0x80000
	s_bfe_u32 s6, s6, 0x3000c
	s_add_i32 s6, s4, s6
	s_and_b32 s7, s6, 0xf8
	s_sub_i32 s4, s4, s7
	s_ashr_i32 s5, s5, 7
	s_lshl_b32 s5, s5, 3
	s_sext_i32_i8 s4, s4
	s_add_i32 s4, s5, s4
	v_writelane_b32 v253, s4, 22
	s_bfe_i32 s4, s6, 0x80000
	s_sext_i32_i16 s4, s4
	s_ashr_i32 s5, s4, 3
	s_lshr_b32 s4, s4, 3
	v_writelane_b32 v253, s5, 23
	s_bfe_i64 s[4:5], s[4:5], 0x100000
	s_lshl_b64 s[4:5], s[4:5], 19
	s_add_u32 s4, s68, s4
	s_addc_u32 s5, s69, s5
	s_add_u32 s6, s4, 0x40000
	s_addc_u32 s7, s5, 0
	v_writelane_b32 v253, s6, 24
	v_readlane_b32 s82, v251, 41
	v_readlane_b32 s83, v251, 42
	v_writelane_b32 v253, s7, 25
	s_add_u32 s6, s4, 0x40080
	v_writelane_b32 v253, s4, 26
	s_addc_u32 s7, s5, 0
	v_readlane_b32 s84, v251, 43
	v_writelane_b32 v253, s5, 27
	s_add_i32 s4, s11, s1
	s_ashr_i32 s5, s4, 31
	s_lshr_b32 s5, s5, 27
	v_writelane_b32 v253, s6, 28
	s_add_i32 s5, s4, s5
	s_add_i32 s1, s3, s1
	v_writelane_b32 v253, s7, 29
	s_and_b32 s6, s5, 0xffe0
	s_sub_i32 s4, s4, s6
	s_bfe_i32 s6, s4, 0x80000
	s_bfe_u32 s6, s6, 0x3000c
	s_add_i32 s6, s4, s6
	s_and_b32 s7, s6, 0xf8
	s_sub_i32 s4, s4, s7
	s_ashr_i32 s5, s5, 5
	s_ashr_i32 s3, s1, 31
	s_lshl_b32 s5, s5, 3
	s_sext_i32_i8 s4, s4
	s_lshr_b32 s3, s3, 27
	s_add_i32 s4, s5, s4
	s_add_i32 s3, s1, s3
	v_writelane_b32 v253, s4, 30
	s_and_b32 s4, s3, 0xffe0
	s_sub_i32 s1, s1, s4
	s_bfe_i32 s4, s1, 0x80000
	s_bfe_u32 s4, s4, 0x3000c
	s_add_i32 s4, s1, s4
	s_and_b32 s5, s4, 0xf8
	s_sub_i32 s1, s1, s5
	s_ashr_i32 s3, s3, 5
	s_bfe_i32 s4, s4, 0x80000
	s_bfe_i32 s5, s6, 0x80000
	s_lshl_b32 s3, s3, 3
	s_sext_i32_i16 s4, s4
	s_sext_i32_i8 s1, s1
	s_sext_i32_i16 s6, s5
	s_add_i32 s48, s3, s1
	s_ashr_i32 s1, s4, 3
	s_lshr_b32 s4, s4, 3
	v_writelane_b32 v253, s1, 31
	s_bfe_i64 s[4:5], s[4:5], 0x100000
	s_ashr_i32 s1, s6, 3
	v_writelane_b32 v253, s1, 32
	s_lshl_b64 s[42:43], s[4:5], 17
	s_ashr_i32 s49, s48, 31
	v_writelane_b32 v253, s42, 33
	s_lshr_b32 s6, s6, 3
	s_lshl_b64 s[10:11], s[48:49], 17
	v_writelane_b32 v253, s43, 34
	v_readlane_b32 s42, v251, 47
	v_readlane_b32 s43, v251, 48
	s_add_u32 s10, s42, s10
	s_addc_u32 s11, s43, s11
	s_add_u32 s42, s10, 0x10000
	v_writelane_b32 v253, s10, 35
	s_addc_u32 s43, s11, 0
	s_bfe_i64 s[6:7], s[6:7], 0x100000
	v_writelane_b32 v253, s11, 36
	v_writelane_b32 v253, s42, 37
	s_lshl_b64 s[6:7], s[6:7], 17
	s_lshl_b64 s[4:5], s[4:5], 19
	v_writelane_b32 v253, s43, 38
	v_writelane_b32 v253, s6, 39
	v_readlane_b32 s85, v251, 44
	v_readlane_b32 s86, v251, 45
	v_writelane_b32 v253, s7, 40
	v_writelane_b32 v253, s4, 41
	v_readlane_b32 s87, v251, 46
	s_barrier
	v_writelane_b32 v253, s5, 42
	s_mov_b32 s4, s48
	v_writelane_b32 v253, s4, 43
	s_nop 1
	v_writelane_b32 v253, s5, 44
	s_lshl_b64 s[4:5], s[48:49], 19
	s_add_u32 s6, s30, s4
	s_addc_u32 s7, s31, s5
	s_add_u32 s10, s6, 0x40000
	v_writelane_b32 v253, s6, 45
	s_addc_u32 s11, s7, 0
	s_add_u32 s4, s34, s4
	v_writelane_b32 v253, s7, 46
	v_writelane_b32 v253, s10, 47
	s_addc_u32 s5, s35, s5
	s_add_u32 s6, s4, 0x40000
	v_writelane_b32 v253, s11, 48
	v_writelane_b32 v253, s4, 49
	s_addc_u32 s7, s5, 0
	s_abs_i32 s1, s2
	v_cvt_f32_u32_e32 v0, s1
	s_sub_i32 s2, 0, s1
	v_writelane_b32 v253, s5, 50
	v_writelane_b32 v253, s6, 51
	v_rcp_iflag_f32_e32 v0, v0
	s_nop 0
	v_writelane_b32 v253, s7, 52
	v_mul_f32_e32 v0, 0x4f7ffffe, v0
	v_cvt_u32_f32_e32 v0, v0
	s_nop 0
	v_readfirstlane_b32 s3, v0
	s_mul_i32 s2, s2, s3
	s_mul_hi_u32 s2, s3, s2
	s_add_i32 s3, s3, s2
	s_lshr_b32 s2, s3, 12
	s_mul_i32 s2, s2, s1
	s_sub_i32 s2, 0x100000, s2
	s_sub_i32 s3, s2, s1
	s_cmp_ge_u32 s2, s1
	s_cselect_b32 s2, s3, s2
	s_sub_i32 s3, s2, s1
	s_cmp_ge_u32 s2, s1
	s_cselect_b32 s1, s3, s2
	s_cmp_lg_u32 s1, 0
	s_cselect_b64 s[2:3], -1, 0
	v_writelane_b32 v253, s2, 53
	s_and_b32 s1, s56, 0x180
	s_nop 0
	v_writelane_b32 v253, s3, 54
	s_add_u32 s2, s36, s1
	s_addc_u32 s3, s37, 0
	v_writelane_b32 v253, s2, 55
	s_add_i32 s1, s56, s12
	s_lshl_b32 s1, s1, 4
	v_writelane_b32 v253, s3, 56
	v_writelane_b32 v253, s1, 57
	s_ashr_i32 s1, s0, 31
	s_lshl_b64 s[2:3], s[0:1], 8
	v_writelane_b32 v253, s2, 58
	s_lshl_b64 s[0:1], s[0:1], 14
	s_nop 0
	v_writelane_b32 v253, s3, 59
	v_writelane_b32 v253, s0, 60
	s_lshl_b64 s[2:3], s[56:57], 14
	s_nop 0
	v_writelane_b32 v253, s1, 61
	s_lshl_b32 s0, s56, 12
	v_writelane_b32 v253, s0, 62
	s_lshl_b32 s0, s12, 12
	v_writelane_b32 v253, s0, 63
	s_lshl_b32 s0, s12, 14
	v_writelane_b32 v254, s0, 0
	s_lshl_b32 s0, s12, 13
	v_writelane_b32 v254, s0, 1
	s_lshl_b32 s0, s12, 6
	v_writelane_b32 v254, s0, 2
	s_lshl_b32 s0, s12, 4
	v_writelane_b32 v254, s0, 3
	s_add_u32 s0, s74, s2
	v_writelane_b32 v254, s2, 4
	s_addc_u32 s1, s75, s3
	s_add_u32 s0, s0, 0x2000000
	v_writelane_b32 v254, s3, 5
	s_addc_u32 s1, s1, 0
	v_writelane_b32 v254, s0, 6
	s_lshl_b64 s[42:43], s[8:9], 14
	s_lshl_b64 s[2:3], s[56:57], 13
	v_writelane_b32 v254, s1, 7
	s_add_u32 s0, s18, s2
	v_writelane_b32 v254, s2, 8
	s_addc_u32 s1, s19, s3
	s_add_u32 s0, s0, 0x2b00000
	v_writelane_b32 v254, s3, 9
	s_addc_u32 s1, s1, 0
	v_writelane_b32 v254, s0, 10
	v_readlane_b32 s2, v251, 49
	v_readlane_b32 s3, v251, 50
	v_writelane_b32 v254, s1, 11
	s_lshl_b64 s[0:1], s[8:9], 13
	v_writelane_b32 v254, s0, 12
	s_nop 1
	v_writelane_b32 v254, s1, 13
	s_lshl_b64 s[0:1], s[8:9], 15
	v_writelane_b32 v254, s0, 14
	s_nop 1
	v_writelane_b32 v254, s1, 15
	s_add_u32 s0, s74, 0x2000000
	s_addc_u32 s1, s75, 0
	v_writelane_b32 v254, s0, 16
	s_movk_i32 s75, 0x1e00
	s_nop 0
	v_writelane_b32 v254, s1, 17
	s_lshl_b64 s[0:1], s[8:9], 16
	v_writelane_b32 v254, s0, 18
	s_nop 1
	v_writelane_b32 v254, s1, 19
	s_lshl_b64 s[0:1], s[8:9], 10
	s_add_u32 s0, s0, s2
	s_addc_u32 s1, s1, s3
	v_writelane_b32 v254, s0, 20
	s_nop 1
	v_writelane_b32 v254, s1, 21
	v_writelane_b32 v254, s46, 22
	s_add_u32 s0, s41, s2
	s_addc_u32 s1, s40, s3
	v_writelane_b32 v254, s47, 23
	v_writelane_b32 v254, s0, 24
	v_cndmask_b32_e64 v197, 0, 1, s[46:47]
	s_mov_b32 s41, 0xfffff
	v_writelane_b32 v254, s1, 25
	s_mov_b32 s0, s56
	v_writelane_b32 v254, s0, 26
	s_mov_b64 s[56:57], 0x100000
	s_nop 0
	v_writelane_b32 v254, s1, 27
	s_add_u32 s0, s2, s44
	s_addc_u32 s1, s3, s45
	v_writelane_b32 v254, s0, 28
	s_add_i32 s73, 0, 0x20204
	s_add_i32 s74, 0, 0x2020c
	v_writelane_b32 v254, s1, 29
	s_add_i32 s0, 0, 0x20400
	v_writelane_b32 v254, s0, 30
	s_add_i32 s0, 0, 0x20080
	v_writelane_b32 v254, s0, 31
	s_add_i32 s0, 0, 0x20084
	v_writelane_b32 v254, s0, 32
	s_add_i32 s0, 0, 0x8800
	v_writelane_b32 v254, s0, 33
	s_mov_b32 s0, s53
	v_writelane_b32 v254, s0, 34
	s_nop 1
	v_writelane_b32 v254, s1, 35
	v_writelane_b32 v254, s97, 36
	v_writelane_b32 v254, s42, 37
	s_nop 1
	v_writelane_b32 v254, s43, 38
	v_writelane_b32 v254, s95, 39
	s_branch .LBB0_142

.Lattn_fast_B:
	s_waitcnt lgkmcnt(1)
	v_mfma_f32_32x32x16_bf16 v[66:81], v[138:141], v[94:97], v[66:81]
	s_waitcnt lgkmcnt(0)
	v_mfma_f32_32x32x16_bf16 v[50:65], v[142:145], v[94:97], v[50:65]
	ds_read_b128 v[138:141], v134 offset:37120
	ds_read_b128 v[142:145], v134 offset:37136
	s_waitcnt lgkmcnt(1)
	s_nop 6
	v_add_f32_e32 v138, v66, v138
	v_add_f32_e32 v137, v67, v139
	s_mov_b32 s0, 0xf149f2ca
	v_add_f32_e32 v139, v68, v140
	v_max3_f32 v66, v138, s0, v137
	v_add_f32_e32 v140, v69, v141
	s_waitcnt lgkmcnt(0)
	v_add_f32_e32 v141, v70, v142
	v_add_f32_e32 v142, v71, v143
	v_add_f32_e32 v143, v72, v144
	v_max3_f32 v66, v66, v139, v140
	v_add_f32_e32 v144, v73, v145
	v_max3_f32 v66, v66, v141, v142
	v_max3_f32 v145, v66, v143, v144
	ds_read_b128 v[66:69], v134 offset:37184
	ds_read_b128 v[70:73], v134 offset:37200
	s_waitcnt lgkmcnt(1)
	v_add_f32_e32 v74, v74, v66
	v_add_f32_e32 v75, v75, v67
	v_add_f32_e32 v76, v76, v68
	v_add_f32_e32 v77, v77, v69
	s_waitcnt lgkmcnt(0)
	v_add_f32_e32 v78, v78, v70
	v_max3_f32 v66, v145, v74, v75
	v_add_f32_e32 v145, v79, v71
	v_add_f32_e32 v148, v80, v72
	v_max3_f32 v66, v66, v76, v77
	v_add_f32_e32 v81, v81, v73
	v_max3_f32 v66, v66, v78, v145
	v_max3_f32 v79, v66, v148, v81
	ds_read_b128 v[66:69], v134 offset:37248
	ds_read_b128 v[70:73], v134 offset:37264
	s_waitcnt lgkmcnt(1)
	v_add_f32_e32 v66, v50, v66
	v_add_f32_e32 v67, v51, v67
	v_add_f32_e32 v68, v52, v68
	v_add_f32_e32 v69, v53, v69
	s_waitcnt lgkmcnt(0)
	v_add_f32_e32 v70, v54, v70
	v_add_f32_e32 v71, v55, v71
	v_add_f32_e32 v72, v56, v72
	v_max3_f32 v50, v79, v66, v67
	v_max3_f32 v50, v50, v68, v69
	v_add_f32_e32 v73, v57, v73
	v_max3_f32 v50, v50, v70, v71
	v_max3_f32 v79, v50, v72, v73
	ds_read_b128 v[50:53], v134 offset:37312
	ds_read_b128 v[54:57], v134 offset:37328
	s_waitcnt lgkmcnt(1)
	v_add_f32_e32 v149, v58, v50
	v_add_f32_e32 v80, v59, v51
	v_max3_f32 v50, v79, v149, v80
	v_add_f32_e32 v79, v60, v52
	v_add_f32_e32 v53, v61, v53
	s_waitcnt lgkmcnt(0)
	v_add_f32_e32 v62, v62, v54
	v_add_f32_e32 v162, v63, v55
	v_add_f32_e32 v163, v64, v56
	v_max3_f32 v50, v50, v79, v53
	v_add_f32_e32 v57, v65, v57
	v_max3_f32 v50, v50, v62, v162
	v_max3_f32 v0, v50, v163, v57
	ds_bpermute_b32 v50, v255, v0
	s_waitcnt lgkmcnt(0)
	v_max3_f32 v63, v136, v0, v50
	v_sub_f32_e32 v0, v138, v63
	v_exp_f32_e32 v164, v0
	v_sub_f32_e32 v0, v66, v63
	v_sub_f32_e32 v52, v139, v63
	v_exp_f32_e32 v165, v0
	v_sub_f32_e32 v0, v137, v63
	v_exp_f32_e32 v166, v52
	v_sub_f32_e32 v52, v68, v63
	v_sub_f32_e32 v56, v141, v63
	v_sub_f32_e32 v53, v53, v63
	v_exp_f32_e32 v50, v0
	v_sub_f32_e32 v0, v67, v63
	v_exp_f32_e32 v167, v52
	v_sub_f32_e32 v52, v140, v63
	v_exp_f32_e32 v140, v56
	v_sub_f32_e32 v56, v70, v63
	v_sub_f32_e32 v60, v143, v63
	v_sub_f32_e32 v67, v76, v63
	v_exp_f32_e32 v76, v53
	v_sub_f32_e32 v53, v78, v63
	v_exp_f32_e32 v141, v56
	v_sub_f32_e32 v56, v142, v63
	v_exp_f32_e32 v142, v60
	v_sub_f32_e32 v60, v72, v63
	v_sub_f32_e32 v66, v74, v63
	v_exp_f32_e32 v170, v53
	v_sub_f32_e32 v53, v62, v63
	v_exp_f32_e32 v0, v0
	v_exp_f32_e32 v143, v60
	v_sub_f32_e32 v60, v144, v63
	v_exp_f32_e32 v144, v66
	v_sub_f32_e32 v66, v149, v63
	v_exp_f32_e32 v171, v53
	v_sub_f32_e32 v53, v145, v63
	v_exp_f32_e32 v149, v66
	v_sub_f32_e32 v66, v75, v63
	v_exp_f32_e32 v78, v53
	v_sub_f32_e32 v53, v162, v63
	v_exp_f32_e32 v54, v52
	v_sub_f32_e32 v52, v69, v63
	v_exp_f32_e32 v68, v66
	v_sub_f32_e32 v66, v80, v63
	v_exp_f32_e32 v80, v53
	v_sub_f32_e32 v53, v148, v63
	v_add_f32_e32 v51, v164, v165
	v_exp_f32_e32 v52, v52
	v_exp_f32_e32 v145, v53
	v_sub_f32_e32 v53, v163, v63
	v_exp_f32_e32 v58, v56
	v_sub_f32_e32 v56, v71, v63
	v_exp_f32_e32 v148, v53
	v_sub_f32_e32 v53, v81, v63
	v_add_f32_e32 v70, v50, v0
	v_add_f32_e32 v71, v51, v1
	v_sub_f32_e32 v65, v136, v63
	v_exp_f32_e32 v136, v53
	v_sub_f32_e32 v53, v57, v63
	v_add_f32_e32 v71, v70, v71
	v_add_f32_e32 v55, v166, v167
	v_exp_f32_e32 v56, v56
	v_exp_f32_e32 v138, v53
	v_add_f32_e32 v70, v54, v52
	v_add_f32_e32 v71, v55, v71
	v_sub_f32_e32 v64, v73, v63
	v_add_f32_e32 v71, v70, v71
	v_add_f32_e32 v59, v140, v141
	v_exp_f32_e32 v60, v60
	v_exp_f32_e32 v64, v64
	v_add_f32_e32 v70, v58, v56
	v_add_f32_e32 v71, v59, v71
	v_add_f32_e32 v61, v142, v143
	v_add_f32_e32 v71, v70, v71
	v_exp_f32_e32 v66, v66
	v_exp_f32_e32 v62, v65
	v_exp_f32_e32 v168, v67
	v_sub_f32_e32 v67, v79, v63
	v_add_f32_e32 v70, v60, v64
	v_add_f32_e32 v71, v61, v71
	v_exp_f32_e32 v169, v67
	v_sub_f32_e32 v67, v77, v63
	v_add_f32_e32 v71, v70, v71
	v_add_f32_e32 v69, v144, v149
	v_exp_f32_e32 v74, v67
	v_add_f32_e32 v70, v68, v66
	v_add_f32_e32 v71, v69, v71
	v_add_f32_e32 v75, v168, v169
	v_add_f32_e32 v71, v70, v71
	v_add_f32_e32 v70, v74, v76
	v_add_f32_e32 v71, v75, v71
	v_add_f32_e32 v79, v170, v171
	v_add_f32_e32 v71, v70, v71
	v_add_f32_e32 v70, v78, v80
	v_add_f32_e32 v71, v79, v71
	v_add_f32_e32 v137, v145, v148
	v_add_f32_e32 v71, v70, v71
	v_add_f32_e32 v70, v136, v138
	v_add_f32_e32 v71, v137, v71
	v_cvt_pk_bf16_f32 v72, v140, v58
	v_add_f32_e32 v65, v70, v71
	v_cvt_pk_bf16_f32 v71, v166, v54
	v_cvt_pk_bf16_f32 v54, v165, v0
	v_add_u32_e32 v0, v132, v122
	v_cvt_pk_bf16_f32 v70, v164, v50
	v_cvt_pk_bf16_f32 v73, v142, v60
	v_cvt_pk_bf16_f32 v58, v144, v68
	v_cvt_pk_bf16_f32 v59, v168, v74
	v_cvt_pk_bf16_f32 v60, v170, v78
	v_cvt_pk_bf16_f32 v55, v167, v52
	v_cvt_pk_bf16_f32 v50, v149, v66
	v_cvt_pk_bf16_f32 v51, v169, v76
	v_cvt_pk_bf16_f32 v52, v171, v80
	ds_read_b128 v[66:69], v0 offset:32256
	ds_read_b128 v[74:77], v0 offset:27648
	ds_read_b128 v[78:81], v0 offset:27680
	v_mul_f32_e32 v16, v62, v16
	v_mul_f32_e32 v17, v62, v17
	v_mul_f32_e32 v14, v62, v14
	v_mul_f32_e32 v15, v62, v15
	v_mul_f32_e32 v12, v62, v12
	v_mul_f32_e32 v13, v62, v13
	v_mul_f32_e32 v10, v62, v10
	v_mul_f32_e32 v11, v62, v11
	v_mul_f32_e32 v8, v62, v8
	v_mul_f32_e32 v9, v62, v9
	v_mul_f32_e32 v6, v62, v6
	v_mul_f32_e32 v7, v62, v7
	v_mul_f32_e32 v4, v62, v4
	v_mul_f32_e32 v5, v62, v5
	v_mul_f32_e32 v2, v62, v2
	v_mul_f32_e32 v3, v62, v3
	v_mul_f32_e32 v32, v62, v32
	v_mul_f32_e32 v33, v62, v33
	v_mul_f32_e32 v30, v62, v30
	v_mul_f32_e32 v31, v62, v31
	v_mul_f32_e32 v28, v62, v28
	v_mul_f32_e32 v29, v62, v29
	v_mul_f32_e32 v26, v62, v26
	v_mul_f32_e32 v27, v62, v27
	v_mul_f32_e32 v24, v62, v24
	v_mul_f32_e32 v25, v62, v25
	v_mul_f32_e32 v22, v62, v22
	v_mul_f32_e32 v23, v62, v23
	v_mul_f32_e32 v20, v62, v20
	v_mul_f32_e32 v21, v62, v21
	v_mul_f32_e32 v18, v62, v18
	v_mul_f32_e32 v19, v62, v19
	s_waitcnt lgkmcnt(2)
	v_mfma_f32_32x32x16_bf16 v[2:17], v[66:69], v[70:73], v[2:17]
	ds_read_b128 v[66:69], v0 offset:32288
	v_cvt_pk_bf16_f32 v61, v145, v136
	v_cvt_pk_bf16_f32 v56, v141, v56
	v_cvt_pk_bf16_f32 v57, v143, v64
	v_cvt_pk_bf16_f32 v53, v148, v138
	v_fma_f32 v133, v133, v62, v65
	v_mov_b32_e32 v136, v63
	s_waitcnt lgkmcnt(2)
	v_mfma_f32_32x32x16_bf16 v[18:33], v[74:77], v[70:73], v[18:33]
	s_waitcnt lgkmcnt(1)
	v_mfma_f32_32x32x16_bf16 v[18:33], v[78:81], v[58:61], v[18:33]
	s_waitcnt lgkmcnt(0)
	v_mfma_f32_32x32x16_bf16 v[2:17], v[66:69], v[58:61], v[2:17]
	ds_read_b128 v[58:61], v0 offset:27712
	ds_read_b128 v[66:69], v0 offset:32320
	s_waitcnt lgkmcnt(1)
	v_mfma_f32_32x32x16_bf16 v[18:33], v[58:61], v[54:57], v[18:33]
	s_waitcnt lgkmcnt(0)
	v_mfma_f32_32x32x16_bf16 v[2:17], v[66:69], v[54:57], v[2:17]
	ds_read_b128 v[54:57], v0 offset:27744
	ds_read_b128 v[58:61], v0 offset:32352
	s_waitcnt lgkmcnt(1)
	v_mfma_f32_32x32x16_bf16 v[18:33], v[54:57], v[50:53], v[18:33]
	s_waitcnt lgkmcnt(0)
	v_mfma_f32_32x32x16_bf16 v[2:17], v[58:61], v[50:53], v[2:17]
	s_branch .LBB0_402
.Lattn_fast_A:
	s_waitcnt lgkmcnt(1)
	v_mfma_f32_32x32x16_bf16 v[66:81], v[138:141], v[94:97], v[66:81]
	s_waitcnt lgkmcnt(0)
	v_mfma_f32_32x32x16_bf16 v[50:65], v[142:145], v[94:97], v[50:65]
	ds_read_b128 v[138:141], v134 offset:36864
	ds_read_b128 v[142:145], v134 offset:36880
	s_waitcnt lgkmcnt(1)
	s_nop 6
	v_add_f32_e32 v137, v66, v138
	v_add_f32_e32 v138, v67, v139
	s_mov_b32 s0, 0xf149f2ca
	v_add_f32_e32 v139, v68, v140
	v_max3_f32 v66, v137, s0, v138
	v_add_f32_e32 v140, v69, v141
	s_waitcnt lgkmcnt(0)
	v_add_f32_e32 v141, v70, v142
	v_add_f32_e32 v142, v71, v143
	v_add_f32_e32 v143, v72, v144
	v_max3_f32 v66, v66, v139, v140
	v_add_f32_e32 v144, v73, v145
	v_max3_f32 v66, v66, v141, v142
	v_max3_f32 v145, v66, v143, v144
	ds_read_b128 v[66:69], v134 offset:36928
	ds_read_b128 v[70:73], v134 offset:36944
	s_waitcnt lgkmcnt(1)
	v_add_f32_e32 v74, v74, v66
	v_add_f32_e32 v75, v75, v67
	v_add_f32_e32 v76, v76, v68
	v_add_f32_e32 v77, v77, v69
	s_waitcnt lgkmcnt(0)
	v_add_f32_e32 v78, v78, v70
	v_max3_f32 v66, v145, v74, v75
	v_add_f32_e32 v145, v79, v71
	v_add_f32_e32 v148, v80, v72
	v_max3_f32 v66, v66, v76, v77
	v_add_f32_e32 v81, v81, v73
	v_max3_f32 v66, v66, v78, v145
	v_max3_f32 v79, v66, v148, v81
	ds_read_b128 v[66:69], v134 offset:36992
	ds_read_b128 v[70:73], v134 offset:37008
	s_waitcnt lgkmcnt(1)
	v_add_f32_e32 v66, v50, v66
	v_add_f32_e32 v67, v51, v67
	v_add_f32_e32 v68, v52, v68
	v_add_f32_e32 v69, v53, v69
	s_waitcnt lgkmcnt(0)
	v_add_f32_e32 v70, v54, v70
	v_add_f32_e32 v71, v55, v71
	v_add_f32_e32 v72, v56, v72
	v_max3_f32 v50, v79, v66, v67
	v_max3_f32 v50, v50, v68, v69
	v_add_f32_e32 v73, v57, v73
	v_max3_f32 v50, v50, v70, v71
	v_max3_f32 v79, v50, v72, v73
	ds_read_b128 v[50:53], v134 offset:37056
	ds_read_b128 v[54:57], v134 offset:37072
	s_waitcnt lgkmcnt(1)
	v_add_f32_e32 v149, v58, v50
	v_add_f32_e32 v59, v59, v51
	v_max3_f32 v50, v79, v149, v59
	v_add_f32_e32 v79, v60, v52
	v_add_f32_e32 v61, v61, v53
	s_waitcnt lgkmcnt(0)
	v_add_f32_e32 v62, v62, v54
	v_add_f32_e32 v55, v63, v55
	v_add_f32_e32 v162, v64, v56
	v_max3_f32 v50, v50, v79, v61
	v_add_f32_e32 v163, v65, v57
	v_max3_f32 v50, v50, v62, v55
	v_max3_f32 v0, v50, v162, v163
	ds_bpermute_b32 v50, v255, v0
	s_waitcnt lgkmcnt(0)
	v_max3_f32 v63, v136, v0, v50
	v_sub_f32_e32 v52, v139, v63
	v_exp_f32_e32 v167, v52
	v_sub_f32_e32 v52, v68, v63
	v_sub_f32_e32 v56, v141, v63
	v_sub_f32_e32 v0, v137, v63
	v_exp_f32_e32 v168, v52
	v_sub_f32_e32 v52, v140, v63
	v_exp_f32_e32 v140, v56
	v_sub_f32_e32 v56, v70, v63
	v_sub_f32_e32 v60, v143, v63
	v_exp_f32_e32 v165, v0
	v_sub_f32_e32 v0, v66, v63
	v_exp_f32_e32 v141, v56
	v_sub_f32_e32 v56, v142, v63
	v_exp_f32_e32 v142, v60
	v_sub_f32_e32 v60, v72, v63
	v_sub_f32_e32 v66, v74, v63
	v_exp_f32_e32 v143, v60
	v_sub_f32_e32 v60, v144, v63
	v_exp_f32_e32 v144, v66
	v_sub_f32_e32 v66, v149, v63
	v_exp_f32_e32 v149, v66
	v_sub_f32_e32 v66, v75, v63
	v_sub_f32_e32 v59, v59, v63
	v_exp_f32_e32 v68, v66
	v_exp_f32_e32 v66, v59
	v_sub_f32_e32 v59, v76, v63
	v_exp_f32_e32 v169, v59
	v_sub_f32_e32 v59, v79, v63
	v_exp_f32_e32 v166, v0
	v_sub_f32_e32 v0, v138, v63
	v_sub_f32_e32 v50, v67, v63
	v_exp_f32_e32 v170, v59
	v_sub_f32_e32 v59, v77, v63
	v_exp_f32_e32 v0, v0
	v_exp_f32_e32 v50, v50
	v_exp_f32_e32 v76, v59
	v_sub_f32_e32 v59, v61, v63
	v_exp_f32_e32 v74, v59
	v_sub_f32_e32 v59, v78, v63
	v_sub_f32_e32 v55, v55, v63
	v_exp_f32_e32 v54, v52
	v_sub_f32_e32 v52, v69, v63
	v_exp_f32_e32 v171, v59
	v_sub_f32_e32 v59, v62, v63
	v_exp_f32_e32 v78, v55
	v_sub_f32_e32 v55, v148, v63
	v_add_f32_e32 v51, v166, v165
	v_exp_f32_e32 v52, v52
	v_exp_f32_e32 v172, v59
	v_sub_f32_e32 v59, v145, v63
	v_exp_f32_e32 v145, v55
	v_sub_f32_e32 v55, v162, v63
	v_exp_f32_e32 v58, v56
	v_sub_f32_e32 v56, v71, v63
	v_exp_f32_e32 v148, v55
	v_sub_f32_e32 v55, v81, v63
	v_add_f32_e32 v70, v50, v0
	v_add_f32_e32 v71, v51, v1
	v_exp_f32_e32 v138, v55
	v_sub_f32_e32 v55, v163, v63
	v_add_f32_e32 v71, v70, v71
	v_sub_f32_e32 v164, v136, v63
	v_add_f32_e32 v53, v168, v167
	v_exp_f32_e32 v56, v56
	v_exp_f32_e32 v136, v55
	v_add_f32_e32 v70, v52, v54
	v_add_f32_e32 v71, v53, v71
	v_sub_f32_e32 v64, v73, v63
	v_add_f32_e32 v71, v70, v71
	v_add_f32_e32 v57, v141, v140
	v_exp_f32_e32 v60, v60
	v_exp_f32_e32 v64, v64
	v_exp_f32_e32 v80, v59
	v_add_f32_e32 v70, v56, v58
	v_add_f32_e32 v71, v57, v71
	v_add_f32_e32 v65, v143, v142
	v_add_f32_e32 v71, v70, v71
	v_add_f32_e32 v70, v64, v60
	v_add_f32_e32 v71, v65, v71
	v_add_f32_e32 v67, v149, v144
	v_add_f32_e32 v71, v70, v71
	v_add_f32_e32 v70, v66, v68
	v_add_f32_e32 v71, v67, v71
	v_add_f32_e32 v75, v170, v169
	v_add_f32_e32 v71, v70, v71
	v_add_f32_e32 v70, v74, v76
	v_add_f32_e32 v71, v75, v71
	v_add_f32_e32 v79, v172, v171
	v_add_f32_e32 v71, v70, v71
	v_add_f32_e32 v70, v78, v80
	v_add_f32_e32 v71, v79, v71
	v_add_f32_e32 v137, v148, v145
	v_add_f32_e32 v71, v70, v71
	v_exp_f32_e32 v62, v164
	v_add_f32_e32 v70, v136, v138
	v_add_f32_e32 v71, v137, v71
	v_cvt_pk_bf16_f32 v72, v140, v58
	v_add_f32_e32 v65, v70, v71
	v_cvt_pk_bf16_f32 v70, v165, v0
	v_add_u32_e32 v0, v132, v122
	v_cvt_pk_bf16_f32 v71, v167, v54
	v_cvt_pk_bf16_f32 v73, v142, v60
	v_cvt_pk_bf16_f32 v58, v144, v68
	v_cvt_pk_bf16_f32 v59, v169, v76
	v_cvt_pk_bf16_f32 v60, v171, v80
	v_cvt_pk_bf16_f32 v54, v166, v50
	v_cvt_pk_bf16_f32 v55, v168, v52
	v_cvt_pk_bf16_f32 v50, v149, v66
	v_cvt_pk_bf16_f32 v51, v170, v74
	v_cvt_pk_bf16_f32 v52, v172, v78
	ds_read_b128 v[66:69], v0 offset:23040
	ds_read_b128 v[74:77], v0 offset:18432
	ds_read_b128 v[78:81], v0 offset:18464
	v_mul_f32_e32 v16, v62, v16
	v_mul_f32_e32 v17, v62, v17
	v_mul_f32_e32 v14, v62, v14
	v_mul_f32_e32 v15, v62, v15
	v_mul_f32_e32 v12, v62, v12
	v_mul_f32_e32 v13, v62, v13
	v_mul_f32_e32 v10, v62, v10
	v_mul_f32_e32 v11, v62, v11
	v_mul_f32_e32 v8, v62, v8
	v_mul_f32_e32 v9, v62, v9
	v_mul_f32_e32 v6, v62, v6
	v_mul_f32_e32 v7, v62, v7
	v_mul_f32_e32 v4, v62, v4
	v_mul_f32_e32 v5, v62, v5
	v_mul_f32_e32 v2, v62, v2
	v_mul_f32_e32 v3, v62, v3
	v_mul_f32_e32 v32, v62, v32
	v_mul_f32_e32 v33, v62, v33
	v_mul_f32_e32 v30, v62, v30
	v_mul_f32_e32 v31, v62, v31
	v_mul_f32_e32 v28, v62, v28
	v_mul_f32_e32 v29, v62, v29
	v_mul_f32_e32 v26, v62, v26
	v_mul_f32_e32 v27, v62, v27
	v_mul_f32_e32 v24, v62, v24
	v_mul_f32_e32 v25, v62, v25
	v_mul_f32_e32 v22, v62, v22
	v_mul_f32_e32 v23, v62, v23
	v_mul_f32_e32 v20, v62, v20
	v_mul_f32_e32 v21, v62, v21
	v_mul_f32_e32 v18, v62, v18
	v_mul_f32_e32 v19, v62, v19
	s_waitcnt lgkmcnt(2)
	v_mfma_f32_32x32x16_bf16 v[2:17], v[66:69], v[70:73], v[2:17]
	ds_read_b128 v[66:69], v0 offset:23072
	v_cvt_pk_bf16_f32 v61, v145, v138
	v_cvt_pk_bf16_f32 v56, v141, v56
	v_cvt_pk_bf16_f32 v57, v143, v64
	v_cvt_pk_bf16_f32 v53, v148, v136
	v_fma_f32 v133, v133, v62, v65
	s_waitcnt lgkmcnt(2)
	v_mfma_f32_32x32x16_bf16 v[18:33], v[74:77], v[70:73], v[18:33]
	v_mov_b32_e32 v136, v63
	s_waitcnt lgkmcnt(1)
	v_mfma_f32_32x32x16_bf16 v[18:33], v[78:81], v[58:61], v[18:33]
	s_waitcnt lgkmcnt(0)
	v_mfma_f32_32x32x16_bf16 v[2:17], v[66:69], v[58:61], v[2:17]
	ds_read_b128 v[58:61], v0 offset:18496
	ds_read_b128 v[66:69], v0 offset:23104
	s_waitcnt lgkmcnt(1)
	v_mfma_f32_32x32x16_bf16 v[18:33], v[58:61], v[54:57], v[18:33]
	s_waitcnt lgkmcnt(0)
	v_mfma_f32_32x32x16_bf16 v[2:17], v[66:69], v[54:57], v[2:17]
	ds_read_b128 v[54:57], v0 offset:18528
	ds_read_b128 v[58:61], v0 offset:23136
	s_waitcnt lgkmcnt(1)
	v_mfma_f32_32x32x16_bf16 v[18:33], v[54:57], v[50:53], v[18:33]
	s_waitcnt lgkmcnt(0)
	v_mfma_f32_32x32x16_bf16 v[2:17], v[58:61], v[50:53], v[2:17]
	s_branch .Lattn_join_A
